# speedup vs baseline: 1.0179x; 1.0179x over previous
; #define MFMA32(a, b, c) __builtin_amdgcn_mfma_f32_32x32x16_bf16((a), (b), (c), 0, 0, 0)
; #define NEG_INF (-__builtin_inff())
; DI int pi_row(int r) { return (r & ~12) | ((r & 4) << 1) | ((r & 8) >> 1); }
; DI void softmax_step(float (&sc)[16], AState& st, const KV& kv) {
;   float mx = NEG_INF;
; #pragma unroll
;   for (int i = 0; i < 16; ++i) mx = fmaxf(mx, sc[i]);
;   mx = fmaxf(mx, __shfl_xor(mx, 32));
;   const float mnew = fmaxf(st.m, mx);
;   const float meff = (mnew == NEG_INF) ? 0.f : mnew;
;   const float alpha = __expf(st.m - meff);
;   float rs = 0.f;
; #pragma unroll
;   for (int i = 0; i < 16; ++i) { sc[i] = __expf(sc[i] - meff); rs += sc[i]; }
;   st.l = st.l * alpha + rs;
;   st.m = mnew;
;   if (__any(alpha != 1.f)) {
; #pragma unroll
;     for (int i = 0; i < 16; ++i) { st.o0[i] *= alpha; st.o1[i] *= alpha; }
; DI void forget_group(const u16* R, const u16* T, const float* esuf, const float* ctot, const float* gh, u16* obuf, int hh, int g8, float kmax2, char* lds) {
;     ...
;         const int prow = pi_row(r) + 32 * tl;
; #pragma unroll
;         for (int ks = 0; ks < 4; ++ks) kv.k[ks] = ld16(sK + prow * FG_KROW + ks * 16 + h2 * 8);
; #pragma unroll
;         for (int dt = 0; dt < 2; ++dt)
; #pragma unroll
;           for (int a = 0; a < 2; ++a) kv.v[dt * 2 + a] = ld16(sV + (dt * 32 + r) * F2_VROW + 32 * tl + a * 16 + h2 * 8);
;         kv.cb[0] = *reinterpret_cast<const f32x4*>(sE + 32 * tl + 8 * h2);
;         kv.cb[1] = *reinterpret_cast<const f32x4*>(sE + 32 * tl + 8 * h2 + 4);
;         kv.cb[2] = *reinterpret_cast<const f32x4*>(sE + 32 * tl + 8 * h2 + 16);
;         kv.cb[3] = *reinterpret_cast<const f32x4*>(sE + 32 * tl + 8 * h2 + 20);
;         const float tot = tp[n0 >> 5];
;         f32x16 s;
; #pragma unroll
;         for (int i = 0; i < 16; ++i) s[i] = carry + kv.cb[i >> 2][i & 3];
; #pragma unroll
;         for (int ks = 0; ks < 4; ++ks) s = MFMA32(kv.k[ks], q[ks], s);
;         float sc[16];
; #pragma unroll
;         for (int i = 0; i < 16; ++i) sc[i] = s[i];
;         if (n0 == t0) {
;           const int nbk = n0 + 8 * h2;
; #pragma unroll
;           for (int i = 0; i < 16; ++i) { const int n = nbk + (i & 7) + 16 * (i >> 3); if (n > tq) sc[i] = NEG_INF; }
;         }
;         carry += tot;
;         softmax_step(sc, st, kv);
;         if (__all((zmax + carry - st.m) < -105.f)) done = true;
.LBB0_690:
	s_mul_i32 s2, s13, 0x4900
	s_xor_b64 s[86:87], s[86:87], -1
	v_add_u32_e32 v114, s2, v113
	s_andn2_b64 vcc, exec, s[86:87]
	s_mov_b64 s[86:87], -1
	s_cbranch_vccnz .LBB0_697
	s_cmp_ge_i32 s94, s23
	s_mov_b64 s[90:91], 0
	s_cbranch_scc1 .LBB0_698
	s_addk_i32 s95, 0xe0
	s_ashr_i32 s90, s95, 5
	s_ashr_i32 s91, s90, 31
	s_lshl_b64 s[90:91], s[90:91], 2
	v_readlane_b32 s2, v254, 24
	s_add_u32 s90, s2, s90
	v_readlane_b32 s2, v254, 27
	v_add_u32_e32 v42, v114, v112
	s_addc_u32 s91, s2, s91
	v_add_u32_e32 v0, v114, v110
	ds_read_b128 v[34:37], v42 offset:18640
	ds_read_b128 v[38:41], v42 offset:18624
	ds_read_b128 v[78:81], v42 offset:18576
	ds_read_b128 v[82:85], v42 offset:18560
	ds_read_b128 v[86:89], v0 offset:4608
	global_load_dword v104, v1, s[90:91]
	s_waitcnt lgkmcnt(4)
	v_pk_add_f32 v[48:49], v[102:103], v[36:37] op_sel_hi:[0,1]
	s_waitcnt lgkmcnt(3)
	v_pk_add_f32 v[44:45], v[102:103], v[40:41] op_sel_hi:[0,1]
	s_waitcnt lgkmcnt(2)
	v_pk_add_f32 v[40:41], v[102:103], v[80:81] op_sel_hi:[0,1]
	s_waitcnt lgkmcnt(1)
	v_pk_add_f32 v[36:37], v[102:103], v[84:85] op_sel_hi:[0,1]
	v_pk_add_f32 v[46:47], v[102:103], v[34:35] op_sel_hi:[0,1]
	v_pk_add_f32 v[42:43], v[102:103], v[38:39] op_sel_hi:[0,1]
	v_pk_add_f32 v[38:39], v[102:103], v[78:79] op_sel_hi:[0,1]
	v_pk_add_f32 v[34:35], v[102:103], v[82:83] op_sel_hi:[0,1]
	ds_read_b128 v[78:81], v0 offset:4640
	ds_read_b128 v[82:85], v0 offset:4672
	s_waitcnt lgkmcnt(2)
	v_mfma_f32_32x32x16_bf16 v[34:49], v[86:89], v[50:53], v[34:49]
	ds_read_b128 v[116:119], v0 offset:4704
	v_add_u32_e32 v0, v114, v111
	s_cmp_lg_u32 s16, s10
	s_waitcnt lgkmcnt(2)
	v_mfma_f32_32x32x16_bf16 v[34:49], v[78:81], v[54:57], v[34:49]
	s_waitcnt lgkmcnt(1)
	v_mfma_f32_32x32x16_bf16 v[34:49], v[82:85], v[58:61], v[34:49]
	ds_read_b128 v[90:93], v0 offset:9280
	ds_read_b128 v[86:89], v0 offset:9312
	ds_read_b128 v[82:85], v0 offset:13888
	ds_read_b128 v[78:81], v0 offset:13920
	s_waitcnt lgkmcnt(4)
	v_mfma_f32_32x32x16_bf16 v[34:49], v[116:119], v[62:65], v[34:49]
	s_cbranch_scc1 .Lmy_fg1_nd
	s_nop 10
	v_cndmask_b32_e64 v0, v34, v184, s[50:51]
	v_cndmask_b32_e64 v35, v184, v35, s[52:53]
	v_cndmask_b32_e64 v34, v0, v34, s[52:53]
	v_cndmask_b32_e64 v36, v36, v184, s[54:55]
	v_cndmask_b32_e64 v37, v37, v184, s[56:57]
	v_cndmask_b32_e64 v38, v38, v184, s[58:59]
	v_cndmask_b32_e64 v39, v39, v184, s[60:61]
	v_cndmask_b32_e64 v40, v40, v184, s[62:63]
	v_cndmask_b32_e64 v41, v41, v184, s[64:65]
	v_cndmask_b32_e64 v42, v42, v184, s[66:67]
	v_cndmask_b32_e64 v43, v43, v184, s[68:69]
	v_cndmask_b32_e64 v44, v44, v184, s[70:71]
	v_cndmask_b32_e64 v45, v45, v184, s[72:73]
	v_cndmask_b32_e64 v46, v46, v184, s[74:75]
	v_cndmask_b32_e64 v47, v47, v184, s[76:77]
	v_cndmask_b32_e64 v48, v48, v184, s[78:79]
	v_cndmask_b32_e64 v49, v49, v184, s[80:81]
	v_max3_f32 v0, v34, s35, v35
	v_max3_f32 v0, v0, v36, v37
	v_max3_f32 v0, v0, v38, v39
	v_max3_f32 v0, v0, v40, v41
	v_max3_f32 v0, v0, v42, v43
	v_max3_f32 v0, v0, v44, v45
	v_max3_f32 v0, v0, v46, v47
	v_max3_f32 v0, v0, v48, v49
	ds_bpermute_b32 v115, v106, v0
	s_waitcnt lgkmcnt(0)
	v_max_f32_e32 v120, v0, v115
	s_branch .Lmy_fg1_go
.Lmy_fg1_nd:
	s_nop 10
	s_waitcnt lgkmcnt(0)
.Lmy_fg1_go:
	v_mov_b32_e32 v116, v109
	v_mov_b32_e32 v115, v120
	v_mov_b32_e32 v0, 1.0

; #define MFMA32(a, b, c) __builtin_amdgcn_mfma_f32_32x32x16_bf16((a), (b), (c), 0, 0, 0)
; #define NEG_INF (-__builtin_inff())
; DI int pi_row(int r) { return (r & ~12) | ((r & 4) << 1) | ((r & 8) >> 1); }
; DI void softmax_step(float (&sc)[16], AState& st, const KV& kv) {
;   float mx = NEG_INF;
; #pragma unroll
;   for (int i = 0; i < 16; ++i) mx = fmaxf(mx, sc[i]);
;   mx = fmaxf(mx, __shfl_xor(mx, 32));
;   const float mnew = fmaxf(st.m, mx);
;   const float meff = (mnew == NEG_INF) ? 0.f : mnew;
;   const float alpha = __expf(st.m - meff);
;   float rs = 0.f;
; #pragma unroll
;   for (int i = 0; i < 16; ++i) { sc[i] = __expf(sc[i] - meff); rs += sc[i]; }
;   st.l = st.l * alpha + rs;
;   st.m = mnew;
;   if (__any(alpha != 1.f)) {
; #pragma unroll
;     for (int i = 0; i < 16; ++i) { st.o0[i] *= alpha; st.o1[i] *= alpha; }
; DI void forget_group(const u16* R, const u16* T, const float* esuf, const float* ctot, const float* gh, u16* obuf, int hh, int g8, float kmax2, char* lds) {
;     ...
;         const int prow = pi_row(r) + 32 * tl;
; #pragma unroll
;         for (int ks = 0; ks < 4; ++ks) kv.k[ks] = ld16(sK + prow * FG_KROW + ks * 16 + h2 * 8);
; #pragma unroll
;         for (int dt = 0; dt < 2; ++dt)
; #pragma unroll
;           for (int a = 0; a < 2; ++a) kv.v[dt * 2 + a] = ld16(sV + (dt * 32 + r) * F2_VROW + 32 * tl + a * 16 + h2 * 8);
;         kv.cb[0] = *reinterpret_cast<const f32x4*>(sE + 32 * tl + 8 * h2);
;         kv.cb[1] = *reinterpret_cast<const f32x4*>(sE + 32 * tl + 8 * h2 + 4);
;         kv.cb[2] = *reinterpret_cast<const f32x4*>(sE + 32 * tl + 8 * h2 + 16);
;         kv.cb[3] = *reinterpret_cast<const f32x4*>(sE + 32 * tl + 8 * h2 + 20);
;         const float tot = tp[n0 >> 5];
;         f32x16 s;
; #pragma unroll
;         for (int i = 0; i < 16; ++i) s[i] = carry + kv.cb[i >> 2][i & 3];
; #pragma unroll
;         for (int ks = 0; ks < 4; ++ks) s = MFMA32(kv.k[ks], q[ks], s);
;         float sc[16];
; #pragma unroll
;         for (int i = 0; i < 16; ++i) sc[i] = s[i];
;         if (n0 == t0) {
;           const int nbk = n0 + 8 * h2;
; #pragma unroll
;           for (int i = 0; i < 16; ++i) { const int n = nbk + (i & 7) + 16 * (i >> 3); if (n > tq) sc[i] = NEG_INF; }
;         }
;         carry += tot;
;         softmax_step(sc, st, kv);
;         if (__all((zmax + carry - st.m) < -105.f)) done = true;
.LBB0_698:
	s_and_b64 vcc, exec, s[90:91]
	s_cbranch_vccnz .LBB0_705
	s_cmp_gt_i32 s94, s23
	s_mov_b64 s[86:87], 0
	s_cbranch_scc1 .LBB0_705
	s_ashr_i32 s86, s94, 5
	s_ashr_i32 s87, s86, 31
	s_lshl_b64 s[86:87], s[86:87], 2
	v_readlane_b32 s2, v254, 24
	s_add_u32 s86, s2, s86
	v_readlane_b32 s2, v254, 27
	v_add_u32_e32 v42, v114, v112
	s_addc_u32 s87, s2, s87
	v_add_u32_e32 v0, v114, v110
	ds_read_b128 v[34:37], v42 offset:18512
	ds_read_b128 v[38:41], v42 offset:18496
	ds_read_b128 v[78:81], v42 offset:18448
	ds_read_b128 v[82:85], v42 offset:18432
	ds_read_b128 v[86:89], v0
	global_load_dword v104, v1, s[86:87]
	s_waitcnt lgkmcnt(4)
	v_pk_add_f32 v[48:49], v[102:103], v[36:37] op_sel_hi:[0,1]
	s_waitcnt lgkmcnt(3)
	v_pk_add_f32 v[44:45], v[102:103], v[40:41] op_sel_hi:[0,1]
	s_waitcnt lgkmcnt(2)
	v_pk_add_f32 v[40:41], v[102:103], v[80:81] op_sel_hi:[0,1]
	s_waitcnt lgkmcnt(1)
	v_pk_add_f32 v[36:37], v[102:103], v[84:85] op_sel_hi:[0,1]
	v_pk_add_f32 v[46:47], v[102:103], v[34:35] op_sel_hi:[0,1]
	v_pk_add_f32 v[42:43], v[102:103], v[38:39] op_sel_hi:[0,1]
	v_pk_add_f32 v[38:39], v[102:103], v[78:79] op_sel_hi:[0,1]
	v_pk_add_f32 v[34:35], v[102:103], v[82:83] op_sel_hi:[0,1]
	ds_read_b128 v[78:81], v0 offset:32
	ds_read_b128 v[116:119], v0 offset:96
	s_waitcnt lgkmcnt(2)
	v_mfma_f32_32x32x16_bf16 v[34:49], v[86:89], v[50:53], v[34:49]
	s_cmp_lg_u32 s12, s10
	s_waitcnt lgkmcnt(1)
	v_mfma_f32_32x32x16_bf16 v[34:49], v[78:81], v[54:57], v[34:49]
	ds_read_b128 v[78:81], v0 offset:64
	v_add_u32_e32 v0, v114, v111
	s_waitcnt lgkmcnt(0)
	v_mfma_f32_32x32x16_bf16 v[34:49], v[78:81], v[58:61], v[34:49]
	ds_read_b128 v[90:93], v0 offset:9216
	ds_read_b128 v[86:89], v0 offset:9248
	ds_read_b128 v[82:85], v0 offset:13824
	ds_read_b128 v[78:81], v0 offset:13856
	v_mfma_f32_32x32x16_bf16 v[34:49], v[116:119], v[62:65], v[34:49]
	s_cbranch_scc1 .Lmy_fg0_nd
	s_nop 10
	v_cndmask_b32_e64 v0, v34, v184, s[50:51]
	v_cndmask_b32_e64 v35, v184, v35, s[52:53]
	v_cndmask_b32_e64 v34, v0, v34, s[52:53]
	v_cndmask_b32_e64 v36, v36, v184, s[54:55]
	v_cndmask_b32_e64 v37, v37, v184, s[56:57]
	v_cndmask_b32_e64 v38, v38, v184, s[58:59]
	v_cndmask_b32_e64 v39, v39, v184, s[60:61]
	v_cndmask_b32_e64 v40, v40, v184, s[62:63]
	v_cndmask_b32_e64 v41, v41, v184, s[64:65]
	v_cndmask_b32_e64 v42, v42, v184, s[66:67]
	v_cndmask_b32_e64 v43, v43, v184, s[68:69]
	v_cndmask_b32_e64 v44, v44, v184, s[70:71]
	v_cndmask_b32_e64 v45, v45, v184, s[72:73]
	v_cndmask_b32_e64 v46, v46, v184, s[74:75]
	v_cndmask_b32_e64 v47, v47, v184, s[76:77]
	v_cndmask_b32_e64 v48, v48, v184, s[78:79]
	v_cndmask_b32_e64 v49, v49, v184, s[80:81]
	v_max3_f32 v0, v34, s35, v35
	v_max3_f32 v0, v0, v36, v37
	v_max3_f32 v0, v0, v38, v39
	v_max3_f32 v0, v0, v40, v41
	v_max3_f32 v0, v0, v42, v43
	v_max3_f32 v0, v0, v44, v45
	v_max3_f32 v0, v0, v46, v47
	v_max3_f32 v0, v0, v48, v49
	ds_bpermute_b32 v114, v106, v0
	s_waitcnt lgkmcnt(0)
	v_max_f32_e32 v120, v0, v114
	s_branch .Lmy_fg0_go

; #define NEG_INF (-__builtin_inff())
; DI void softmax_step(float (&sc)[16], AState& st, const KV& kv) {
;     ...
;   const float mnew = fmaxf(st.m, mx);
;   const float meff = (mnew == NEG_INF) ? 0.f : mnew;
;   const float alpha = __expf(st.m - meff);
;   float rs = 0.f;
; #pragma unroll
;   for (int i = 0; i < 16; ++i) { sc[i] = __expf(sc[i] - meff); rs += sc[i]; }
;   st.l = st.l * alpha + rs;
;   st.m = mnew;
.Lmy_fg0_go:
	v_mov_b32_e32 v115, v109
	v_mov_b32_e32 v114, v120
	v_mov_b32_e32 v0, 1.0

; DI void topk_query(const float* impH, const float* linv, u32* selm, int t) {
;     ...
;   for (int j = 0; j < 4; ++j) {
;     const int b = lane + 64 * j;
;     key[j] = 0; cand[j] = false;
;     if (cur <= 15) sel[j] = (b <= cur);
;     else {
;       sel[j] = (b == 0) || (b == cur) || (b == cur - 1);
;       if (b >= 1 && b <= cur - 2) {
;         float v = impH[((size_t)0 * SEQ + t) * 256 + b] * linv[(size_t)0 * SEQ + t];
;         v += impH[((size_t)1 * SEQ + t) * 256 + b] * linv[(size_t)1 * SEQ + t];
;         v += impH[((size_t)2 * SEQ + t) * 256 + b] * linv[(size_t)2 * SEQ + t];
;         v += impH[((size_t)3 * SEQ + t) * 256 + b] * linv[(size_t)3 * SEQ + t];
;         key[j] = __float_as_uint(v);
;         cand[j] = true;
;       }
.Lmy_tk_big:
	s_add_i32 s79, s56, 0
	s_lshl_b32 s79, s79, 10
	s_add_u32 s100, s0, s79
	s_addc_u32 s101, s1, 0
	global_load_dword v6, v17, s[100:101]
	global_load_dword v7, v17, s[100:101] offset:256
	global_load_dword v8, v17, s[100:101] offset:512
	global_load_dword v9, v17, s[100:101] offset:768
	s_add_u32 s100, s100, 0x1000000
	s_addc_u32 s101, s101, 0
	global_load_dword v10, v17, s[100:101]
	global_load_dword v11, v17, s[100:101] offset:256
	global_load_dword v12, v17, s[100:101] offset:512
	global_load_dword v13, v17, s[100:101] offset:768
	s_add_u32 s100, s100, 0x1000000
	s_addc_u32 s101, s101, 0
	global_load_dword v64, v17, s[100:101]
	global_load_dword v65, v17, s[100:101] offset:256
	global_load_dword v66, v17, s[100:101] offset:512
	global_load_dword v67, v17, s[100:101] offset:768
	s_add_u32 s100, s100, 0x1000000
	s_addc_u32 s101, s101, 0
	global_load_dword v68, v17, s[100:101]
	global_load_dword v69, v17, s[100:101] offset:256
	global_load_dword v70, v17, s[100:101] offset:512
	global_load_dword v71, v17, s[100:101] offset:768
	s_lshl_b32 s79, s56, 2
	s_add_u32 s100, s96, s79
	s_addc_u32 s101, s97, 0
	global_load_dwordx4 v[72:75], v1, s[100:101]
	s_add_u32 s100, s100, 0x10000
	s_addc_u32 s101, s101, 0
	global_load_dwordx4 v[76:79], v1, s[100:101]
	s_add_u32 s100, s100, 0x10000
	s_addc_u32 s101, s101, 0
	global_load_dwordx4 v[2:5], v1, s[100:101]
	s_add_u32 s100, s100, 0x10000
	s_addc_u32 s101, s101, 0
	global_load_dwordx4 v[14:17], v1, s[100:101]
	s_waitcnt vmcnt(0)
	v_readfirstlane_b32 s44, v72
	v_readfirstlane_b32 s45, v73
	v_readfirstlane_b32 s46, v74
	v_readfirstlane_b32 s47, v75
	v_readfirstlane_b32 s48, v76
	v_readfirstlane_b32 s49, v77
	v_readfirstlane_b32 s50, v78
	v_readfirstlane_b32 s51, v79
	v_readfirstlane_b32 s60, v2
	v_readfirstlane_b32 s61, v3
	v_readfirstlane_b32 s62, v4
	v_readfirstlane_b32 s63, v5
	v_readfirstlane_b32 s64, v14
	v_readfirstlane_b32 s65, v15
	v_readfirstlane_b32 s66, v16
	v_readfirstlane_b32 s67, v17
	v_lshlrev_b32_e32 v17, 2, v0
	s_add_i32 s57, s78, -2
	v_mov_b32_e32 v15, 0
	v_add_u32_e32 v14, -1, v0
	v_cmp_gt_u32_e32 vcc, s57, v14
	s_nop 1
	v_cndmask_b32_e64 v14, 0, 1, vcc
	v_or_b32_e32 v15, v15, v14
	v_add_u32_e32 v14, 63, v0
	v_cmp_gt_u32_e32 vcc, s57, v14
	s_nop 1
	v_cndmask_b32_e64 v14, 0, 2, vcc
	v_or_b32_e32 v15, v15, v14
	v_add_u32_e32 v14, 127, v0
	v_cmp_gt_u32_e32 vcc, s57, v14
	s_nop 1
	v_cndmask_b32_e64 v14, 0, 4, vcc
	v_or_b32_e32 v15, v15, v14
	v_add_u32_e32 v14, 191, v0
	v_cmp_gt_u32_e32 vcc, s57, v14
	s_nop 1
	v_cndmask_b32_e64 v14, 0, 8, vcc
	v_or_b32_e32 v15, v15, v14
	v_mul_f32_e32 v10, s48, v10
	v_mul_f32_e32 v11, s48, v11
	v_mul_f32_e32 v12, s48, v12
	v_mul_f32_e32 v13, s48, v13
	v_fma_f32 v2, v6, s44, v10
	v_fma_f32 v3, v7, s44, v11
	v_fma_f32 v4, v8, s44, v12
	v_fma_f32 v5, v9, s44, v13
	v_fma_f32 v2, v64, s60, v2
	v_fma_f32 v3, v65, s60, v3
	v_fma_f32 v4, v66, s60, v4
	v_fma_f32 v5, v67, s60, v5
	v_mul_f32_e32 v68, s64, v68
	v_mul_f32_e32 v69, s64, v69
	v_mul_f32_e32 v70, s64, v70
	v_mul_f32_e32 v71, s64, v71
	v_add_f32_e32 v2, v2, v68
	v_add_f32_e32 v3, v3, v69
	v_add_f32_e32 v4, v4, v70
	v_add_f32_e32 v5, v5, v71
	v_bfe_i32 v14, v15, 0, 1
	v_and_b32_e32 v2, v2, v14
	v_bfe_i32 v14, v15, 1, 1
	v_and_b32_e32 v3, v3, v14
	v_bfe_i32 v14, v15, 2, 1
	v_and_b32_e32 v4, v4, v14
	v_bfe_i32 v14, v15, 3, 1
	v_and_b32_e32 v5, v5, v14
	s_add_i32 s79, s56, 1
	s_lshl_b32 s79, s79, 10
	s_add_u32 s100, s0, s79
	s_addc_u32 s101, s1, 0
	global_load_dword v6, v17, s[100:101]
	global_load_dword v7, v17, s[100:101] offset:256
	global_load_dword v8, v17, s[100:101] offset:512
	global_load_dword v9, v17, s[100:101] offset:768
	s_add_u32 s100, s100, 0x1000000
	s_addc_u32 s101, s101, 0
	global_load_dword v10, v17, s[100:101]
	global_load_dword v11, v17, s[100:101] offset:256
	global_load_dword v12, v17, s[100:101] offset:512
	global_load_dword v13, v17, s[100:101] offset:768
	s_add_u32 s100, s100, 0x1000000
	s_addc_u32 s101, s101, 0
	global_load_dword v64, v17, s[100:101]
	global_load_dword v65, v17, s[100:101] offset:256
	global_load_dword v66, v17, s[100:101] offset:512
	global_load_dword v67, v17, s[100:101] offset:768
	s_add_u32 s100, s100, 0x1000000
	s_addc_u32 s101, s101, 0
	global_load_dword v68, v17, s[100:101]
	global_load_dword v69, v17, s[100:101] offset:256
	global_load_dword v70, v17, s[100:101] offset:512
	global_load_dword v71, v17, s[100:101] offset:768
	s_mov_b32 s2, 31
	s_mov_b32 s10, 0
	s_mov_b32 s11, 13
	s_add_i32 s57, s78, -2

; DI void topk_query(const float* impH, const float* linv, u32* selm, int t) {
;     ...
;   for (int j = 0; j < 4; ++j) {
;     const int b = lane + 64 * j;
;     key[j] = 0; cand[j] = false;
;     if (cur <= 15) sel[j] = (b <= cur);
;     else {
;       sel[j] = (b == 0) || (b == cur) || (b == cur - 1);
;       if (b >= 1 && b <= cur - 2) {
;         float v = impH[((size_t)0 * SEQ + t) * 256 + b] * linv[(size_t)0 * SEQ + t];
;         v += impH[((size_t)1 * SEQ + t) * 256 + b] * linv[(size_t)1 * SEQ + t];
;         v += impH[((size_t)2 * SEQ + t) * 256 + b] * linv[(size_t)2 * SEQ + t];
;         v += impH[((size_t)3 * SEQ + t) * 256 + b] * linv[(size_t)3 * SEQ + t];
;         key[j] = __float_as_uint(v);
;         cand[j] = true;
;       }
.Lmy_tk_out0:
	v_writelane_b32 v16, s52, 0
	v_writelane_b32 v16, s53, 1
	v_writelane_b32 v16, s54, 2
	v_writelane_b32 v16, s55, 3
	v_writelane_b32 v16, s58, 4
	v_writelane_b32 v16, s59, 5
	v_writelane_b32 v16, s68, 6
	v_writelane_b32 v16, s69, 7
	s_waitcnt vmcnt(0)
	v_mul_f32_e32 v10, s49, v10
	v_mul_f32_e32 v11, s49, v11
	v_mul_f32_e32 v12, s49, v12
	v_mul_f32_e32 v13, s49, v13
	v_fma_f32 v2, v6, s45, v10
	v_fma_f32 v3, v7, s45, v11
	v_fma_f32 v4, v8, s45, v12
	v_fma_f32 v5, v9, s45, v13
	v_fma_f32 v2, v64, s61, v2
	v_fma_f32 v3, v65, s61, v3
	v_fma_f32 v4, v66, s61, v4
	v_fma_f32 v5, v67, s61, v5
	v_mul_f32_e32 v68, s65, v68
	v_mul_f32_e32 v69, s65, v69
	v_mul_f32_e32 v70, s65, v70
	v_mul_f32_e32 v71, s65, v71
	v_add_f32_e32 v2, v2, v68
	v_add_f32_e32 v3, v3, v69
	v_add_f32_e32 v4, v4, v70
	v_add_f32_e32 v5, v5, v71
	v_bfe_i32 v14, v15, 0, 1
	v_and_b32_e32 v2, v2, v14
	v_bfe_i32 v14, v15, 1, 1
	v_and_b32_e32 v3, v3, v14
	v_bfe_i32 v14, v15, 2, 1
	v_and_b32_e32 v4, v4, v14
	v_bfe_i32 v14, v15, 3, 1
	v_and_b32_e32 v5, v5, v14
	s_add_i32 s79, s56, 2
	s_lshl_b32 s79, s79, 10
	s_add_u32 s100, s0, s79
	s_addc_u32 s101, s1, 0
	global_load_dword v6, v17, s[100:101]
	global_load_dword v7, v17, s[100:101] offset:256
	global_load_dword v8, v17, s[100:101] offset:512
	global_load_dword v9, v17, s[100:101] offset:768
	s_add_u32 s100, s100, 0x1000000
	s_addc_u32 s101, s101, 0
	global_load_dword v10, v17, s[100:101]
	global_load_dword v11, v17, s[100:101] offset:256
	global_load_dword v12, v17, s[100:101] offset:512
	global_load_dword v13, v17, s[100:101] offset:768
	s_add_u32 s100, s100, 0x1000000
	s_addc_u32 s101, s101, 0
	global_load_dword v64, v17, s[100:101]
	global_load_dword v65, v17, s[100:101] offset:256
	global_load_dword v66, v17, s[100:101] offset:512
	global_load_dword v67, v17, s[100:101] offset:768
	s_add_u32 s100, s100, 0x1000000
	s_addc_u32 s101, s101, 0
	global_load_dword v68, v17, s[100:101]
	global_load_dword v69, v17, s[100:101] offset:256
	global_load_dword v70, v17, s[100:101] offset:512
	global_load_dword v71, v17, s[100:101] offset:768
	s_mov_b32 s2, 31
	s_mov_b32 s10, 0
	s_mov_b32 s11, 13
	s_add_i32 s57, s78, -2

; DI void topk_query(const float* impH, const float* linv, u32* selm, int t) {
;     ...
;   for (int j = 0; j < 4; ++j) {
;     const int b = lane + 64 * j;
;     key[j] = 0; cand[j] = false;
;     if (cur <= 15) sel[j] = (b <= cur);
;     else {
;       sel[j] = (b == 0) || (b == cur) || (b == cur - 1);
;       if (b >= 1 && b <= cur - 2) {
;         float v = impH[((size_t)0 * SEQ + t) * 256 + b] * linv[(size_t)0 * SEQ + t];
;         v += impH[((size_t)1 * SEQ + t) * 256 + b] * linv[(size_t)1 * SEQ + t];
;         v += impH[((size_t)2 * SEQ + t) * 256 + b] * linv[(size_t)2 * SEQ + t];
;         v += impH[((size_t)3 * SEQ + t) * 256 + b] * linv[(size_t)3 * SEQ + t];
;         key[j] = __float_as_uint(v);
;         cand[j] = true;
;       }
.Lmy_tk_out1:
	v_writelane_b32 v16, s52, 8
	v_writelane_b32 v16, s53, 9
	v_writelane_b32 v16, s54, 10
	v_writelane_b32 v16, s55, 11
	v_writelane_b32 v16, s58, 12
	v_writelane_b32 v16, s59, 13
	v_writelane_b32 v16, s68, 14
	v_writelane_b32 v16, s69, 15
	s_waitcnt vmcnt(0)
	v_mul_f32_e32 v10, s50, v10
	v_mul_f32_e32 v11, s50, v11
	v_mul_f32_e32 v12, s50, v12
	v_mul_f32_e32 v13, s50, v13
	v_fma_f32 v2, v6, s46, v10
	v_fma_f32 v3, v7, s46, v11
	v_fma_f32 v4, v8, s46, v12
	v_fma_f32 v5, v9, s46, v13
	v_fma_f32 v2, v64, s62, v2
	v_fma_f32 v3, v65, s62, v3
	v_fma_f32 v4, v66, s62, v4
	v_fma_f32 v5, v67, s62, v5
	v_mul_f32_e32 v68, s66, v68
	v_mul_f32_e32 v69, s66, v69
	v_mul_f32_e32 v70, s66, v70
	v_mul_f32_e32 v71, s66, v71
	v_add_f32_e32 v2, v2, v68
	v_add_f32_e32 v3, v3, v69
	v_add_f32_e32 v4, v4, v70
	v_add_f32_e32 v5, v5, v71
	v_bfe_i32 v14, v15, 0, 1
	v_and_b32_e32 v2, v2, v14
	v_bfe_i32 v14, v15, 1, 1
	v_and_b32_e32 v3, v3, v14
	v_bfe_i32 v14, v15, 2, 1
	v_and_b32_e32 v4, v4, v14
	v_bfe_i32 v14, v15, 3, 1
	v_and_b32_e32 v5, v5, v14
	s_add_i32 s79, s56, 3
	s_lshl_b32 s79, s79, 10
	s_add_u32 s100, s0, s79
	s_addc_u32 s101, s1, 0
	global_load_dword v6, v17, s[100:101]
	global_load_dword v7, v17, s[100:101] offset:256
	global_load_dword v8, v17, s[100:101] offset:512
	global_load_dword v9, v17, s[100:101] offset:768
	s_add_u32 s100, s100, 0x1000000
	s_addc_u32 s101, s101, 0
	global_load_dword v10, v17, s[100:101]
	global_load_dword v11, v17, s[100:101] offset:256
	global_load_dword v12, v17, s[100:101] offset:512
	global_load_dword v13, v17, s[100:101] offset:768
	s_add_u32 s100, s100, 0x1000000
	s_addc_u32 s101, s101, 0
	global_load_dword v64, v17, s[100:101]
	global_load_dword v65, v17, s[100:101] offset:256
	global_load_dword v66, v17, s[100:101] offset:512
	global_load_dword v67, v17, s[100:101] offset:768
	s_add_u32 s100, s100, 0x1000000
	s_addc_u32 s101, s101, 0
	global_load_dword v68, v17, s[100:101]
	global_load_dword v69, v17, s[100:101] offset:256
	global_load_dword v70, v17, s[100:101] offset:512
	global_load_dword v71, v17, s[100:101] offset:768
	s_mov_b32 s2, 31
	s_mov_b32 s10, 0
	s_mov_b32 s11, 13
	s_add_i32 s57, s78, -2

; DI void topk_query(const float* impH, const float* linv, u32* selm, int t) {
;     ...
;   for (int j = 0; j < 4; ++j) {
;     const int b = lane + 64 * j;
;     key[j] = 0; cand[j] = false;
;     if (cur <= 15) sel[j] = (b <= cur);
;     else {
;       sel[j] = (b == 0) || (b == cur) || (b == cur - 1);
;       if (b >= 1 && b <= cur - 2) {
;         float v = impH[((size_t)0 * SEQ + t) * 256 + b] * linv[(size_t)0 * SEQ + t];
;         v += impH[((size_t)1 * SEQ + t) * 256 + b] * linv[(size_t)1 * SEQ + t];
;         v += impH[((size_t)2 * SEQ + t) * 256 + b] * linv[(size_t)2 * SEQ + t];
;         v += impH[((size_t)3 * SEQ + t) * 256 + b] * linv[(size_t)3 * SEQ + t];
;         key[j] = __float_as_uint(v);
;         cand[j] = true;
;       }
.Lmy_tk_out2:
	v_writelane_b32 v16, s52, 16
	v_writelane_b32 v16, s53, 17
	v_writelane_b32 v16, s54, 18
	v_writelane_b32 v16, s55, 19
	v_writelane_b32 v16, s58, 20
	v_writelane_b32 v16, s59, 21
	v_writelane_b32 v16, s68, 22
	v_writelane_b32 v16, s69, 23
	s_waitcnt vmcnt(0)
	v_mul_f32_e32 v10, s51, v10
	v_mul_f32_e32 v11, s51, v11
	v_mul_f32_e32 v12, s51, v12
	v_mul_f32_e32 v13, s51, v13
	v_fma_f32 v2, v6, s47, v10
	v_fma_f32 v3, v7, s47, v11
	v_fma_f32 v4, v8, s47, v12
	v_fma_f32 v5, v9, s47, v13
	v_fma_f32 v2, v64, s63, v2
	v_fma_f32 v3, v65, s63, v3
	v_fma_f32 v4, v66, s63, v4
	v_fma_f32 v5, v67, s63, v5
	v_mul_f32_e32 v68, s67, v68
	v_mul_f32_e32 v69, s67, v69
	v_mul_f32_e32 v70, s67, v70
	v_mul_f32_e32 v71, s67, v71
	v_add_f32_e32 v2, v2, v68
	v_add_f32_e32 v3, v3, v69
	v_add_f32_e32 v4, v4, v70
	v_add_f32_e32 v5, v5, v71
	v_bfe_i32 v14, v15, 0, 1
	v_and_b32_e32 v2, v2, v14
	v_bfe_i32 v14, v15, 1, 1
	v_and_b32_e32 v3, v3, v14
	v_bfe_i32 v14, v15, 2, 1
	v_and_b32_e32 v4, v4, v14
	v_bfe_i32 v14, v15, 3, 1
	v_and_b32_e32 v5, v5, v14
	s_mov_b32 s2, 31
	s_mov_b32 s10, 0
	s_mov_b32 s11, 13
	s_add_i32 s57, s78, -2

; __global__ void __launch_bounds__(512, 2) mega(Params P) {
;     ...
;           for (int ai = 0; ai < 2; ++ai)
; #pragma unroll
;             for (int m = 0; m < 4; ++m) {
;               const int row = pm * 256 + ai * 128 + wr * 64 + m * 16 + fr;
; #pragma unroll
;               for (int bj = 0; bj < 2; ++bj)
; #pragma unroll
;                 for (int n = 0; n < 2; ++n) {
;                   const int col = pn * 256 + bj * 128 + wc * 32 + n * 16 + fq * 4;
;                   f32x4* hp = reinterpret_cast<f32x4*>(H + (size_t)row * DM + col);
;                   f32x4 hv = *hp;
;                   const acc4 v = acc[ai][bj][m][n];
;                   hv[0] += v[0]; hv[1] += v[1]; hv[2] += v[2]; hv[3] += v[3];
;                   *hp = hv;
;                 }
;               __builtin_amdgcn_sched_barrier(0);
;             }
.LBB0_1250:
	s_lshl_b32 s10, s60, 8
	s_mov_b32 s23, s59
	v_lshl_add_u32 v130, s23, 8, v130
	v_lshl_or_b32 v0, v0, 2, s10
	v_lshl_or_b32 v134, s11, 5, v0
	v_readlane_b32 s44, v255, 4
	v_readlane_b32 s56, v255, 16
	v_readlane_b32 s57, v255, 17
	s_mov_b32 s16, s60
	v_readlane_b32 s45, v255, 5
	v_readlane_b32 s46, v255, 6
	v_readlane_b32 s47, v255, 7
	v_readlane_b32 s48, v255, 8
	v_readlane_b32 s49, v255, 9
	v_readlane_b32 s50, v255, 10
	v_readlane_b32 s51, v255, 11
	v_readlane_b32 s52, v255, 12
	v_readlane_b32 s53, v255, 13
	v_readlane_b32 s54, v255, 14
	v_readlane_b32 s55, v255, 15
	v_readlane_b32 s58, v255, 18
	v_readlane_b32 s59, v255, 19
	v_lshlrev_b32_e32 v131, 12, v130
	v_lshl_add_u32 v131, v134, 2, v131
	s_mov_b64 s[100:101], s[56:57]
	global_load_dwordx4 v[136:139], v131, s[100:101]
	global_load_dwordx4 v[140:143], v131, s[100:101] offset:64
	global_load_dwordx4 v[144:147], v131, s[100:101] offset:512
	global_load_dwordx4 v[148:151], v131, s[100:101] offset:576
	s_add_u32 s100, s100, 0x10000
	s_addc_u32 s101, s101, 0
	global_load_dwordx4 v[152:155], v131, s[100:101]
	global_load_dwordx4 v[160:163], v131, s[100:101] offset:64
	global_load_dwordx4 v[170:173], v131, s[100:101] offset:512
	global_load_dwordx4 v[174:177], v131, s[100:101] offset:576
	s_add_u32 s100, s100, 0x10000
	s_addc_u32 s101, s101, 0
	global_load_dwordx4 v[190:193], v131, s[100:101]
	global_load_dwordx4 v[194:197], v131, s[100:101] offset:64
	global_load_dwordx4 v[198:201], v131, s[100:101] offset:512
	global_load_dwordx4 v[202:205], v131, s[100:101] offset:576
	s_add_u32 s100, s100, 0x10000
	s_addc_u32 s101, s101, 0
	global_load_dwordx4 v[206:209], v131, s[100:101]
	global_load_dwordx4 v[210:213], v131, s[100:101] offset:64
	global_load_dwordx4 v[214:217], v131, s[100:101] offset:512
	global_load_dwordx4 v[218:221], v131, s[100:101] offset:576
	s_waitcnt vmcnt(0)
	v_pk_add_f32 v[126:127], v[126:127], v[136:137]
	v_pk_add_f32 v[128:129], v[128:129], v[138:139]
	v_pk_add_f32 v[118:119], v[118:119], v[140:141]
	v_pk_add_f32 v[120:121], v[120:121], v[142:143]
	v_pk_add_f32 v[122:123], v[122:123], v[144:145]
	v_pk_add_f32 v[124:125], v[124:125], v[146:147]
	v_pk_add_f32 v[114:115], v[114:115], v[148:149]
	v_pk_add_f32 v[116:117], v[116:117], v[150:151]
	v_pk_add_f32 v[110:111], v[110:111], v[152:153]
	v_pk_add_f32 v[112:113], v[112:113], v[154:155]
	v_pk_add_f32 v[102:103], v[102:103], v[160:161]
	v_pk_add_f32 v[104:105], v[104:105], v[162:163]
	v_pk_add_f32 v[106:107], v[106:107], v[170:171]
	v_pk_add_f32 v[108:109], v[108:109], v[172:173]
	v_pk_add_f32 v[98:99], v[98:99], v[174:175]
	v_pk_add_f32 v[100:101], v[100:101], v[176:177]
	v_pk_add_f32 v[94:95], v[94:95], v[190:191]
	v_pk_add_f32 v[96:97], v[96:97], v[192:193]
	v_pk_add_f32 v[86:87], v[86:87], v[194:195]
	v_pk_add_f32 v[88:89], v[88:89], v[196:197]
	v_pk_add_f32 v[90:91], v[90:91], v[198:199]
	v_pk_add_f32 v[92:93], v[92:93], v[200:201]
	v_pk_add_f32 v[82:83], v[82:83], v[202:203]
	v_pk_add_f32 v[84:85], v[84:85], v[204:205]
	v_pk_add_f32 v[78:79], v[78:79], v[206:207]
	v_pk_add_f32 v[80:81], v[80:81], v[208:209]
	v_pk_add_f32 v[70:71], v[70:71], v[210:211]
	v_pk_add_f32 v[72:73], v[72:73], v[212:213]
	v_pk_add_f32 v[74:75], v[74:75], v[214:215]
	v_pk_add_f32 v[76:77], v[76:77], v[216:217]
	v_pk_add_f32 v[66:67], v[66:67], v[218:219]
	v_pk_add_f32 v[68:69], v[68:69], v[220:221]
	s_add_u32 s100, s100, 0x50000
	s_addc_u32 s101, s101, 0
	global_load_dwordx4 v[136:139], v131, s[100:101]
	global_load_dwordx4 v[140:143], v131, s[100:101] offset:64
	global_load_dwordx4 v[144:147], v131, s[100:101] offset:512
	global_load_dwordx4 v[148:151], v131, s[100:101] offset:576
	s_add_u32 s100, s100, 0x10000
	s_addc_u32 s101, s101, 0
	global_load_dwordx4 v[152:155], v131, s[100:101]
	global_load_dwordx4 v[160:163], v131, s[100:101] offset:64
	global_load_dwordx4 v[170:173], v131, s[100:101] offset:512
	global_load_dwordx4 v[174:177], v131, s[100:101] offset:576
	s_add_u32 s100, s100, 0x10000
	s_addc_u32 s101, s101, 0
	global_load_dwordx4 v[190:193], v131, s[100:101]
	global_load_dwordx4 v[194:197], v131, s[100:101] offset:64
	global_load_dwordx4 v[198:201], v131, s[100:101] offset:512
	global_load_dwordx4 v[202:205], v131, s[100:101] offset:576
	s_add_u32 s100, s100, 0x10000
	s_addc_u32 s101, s101, 0
	global_load_dwordx4 v[206:209], v131, s[100:101]
	global_load_dwordx4 v[210:213], v131, s[100:101] offset:64
	global_load_dwordx4 v[214:217], v131, s[100:101] offset:512
	global_load_dwordx4 v[218:221], v131, s[100:101] offset:576
	s_sub_u32 s100, s100, 0xb0000
	s_subb_u32 s101, s101, 0
	global_store_dwordx4 v131, v[126:129], s[100:101]
	global_store_dwordx4 v131, v[118:121], s[100:101] offset:64
	global_store_dwordx4 v131, v[122:125], s[100:101] offset:512
	global_store_dwordx4 v131, v[114:117], s[100:101] offset:576
	s_add_u32 s100, s100, 0x10000
	s_addc_u32 s101, s101, 0
	global_store_dwordx4 v131, v[110:113], s[100:101]
	global_store_dwordx4 v131, v[102:105], s[100:101] offset:64
	global_store_dwordx4 v131, v[106:109], s[100:101] offset:512
	global_store_dwordx4 v131, v[98:101], s[100:101] offset:576
	s_add_u32 s100, s100, 0x10000
	s_addc_u32 s101, s101, 0
	global_store_dwordx4 v131, v[94:97], s[100:101]
	global_store_dwordx4 v131, v[86:89], s[100:101] offset:64
	global_store_dwordx4 v131, v[90:93], s[100:101] offset:512
	global_store_dwordx4 v131, v[82:85], s[100:101] offset:576
	s_add_u32 s100, s100, 0x10000
	s_addc_u32 s101, s101, 0
	global_store_dwordx4 v131, v[78:81], s[100:101]
	global_store_dwordx4 v131, v[70:73], s[100:101] offset:64
	global_store_dwordx4 v131, v[74:77], s[100:101] offset:512
	global_store_dwordx4 v131, v[66:69], s[100:101] offset:576
	s_waitcnt vmcnt(0)
; __global__ void __launch_bounds__(512, 2) mega(Params P) {
;     ...
;           for (int ai = 0; ai < 2; ++ai)
; #pragma unroll
;             for (int m = 0; m < 4; ++m) {
;               const int row = pm * 256 + ai * 128 + wr * 64 + m * 16 + fr;
; #pragma unroll
;               for (int bj = 0; bj < 2; ++bj)
; #pragma unroll
;                 for (int n = 0; n < 2; ++n) {
;                   const int col = pn * 256 + bj * 128 + wc * 32 + n * 16 + fq * 4;
;                   f32x4* hp = reinterpret_cast<f32x4*>(H + (size_t)row * DM + col);
;                   f32x4 hv = *hp;
;                   const acc4 v = acc[ai][bj][m][n];
;                   hv[0] += v[0]; hv[1] += v[1]; hv[2] += v[2]; hv[3] += v[3];
;                   *hp = hv;
;                 }
;               __builtin_amdgcn_sched_barrier(0);
;             }
	v_pk_add_f32 v[62:63], v[62:63], v[136:137]
	v_pk_add_f32 v[64:65], v[64:65], v[138:139]
	v_pk_add_f32 v[58:59], v[58:59], v[140:141]
	v_pk_add_f32 v[60:61], v[60:61], v[142:143]
	v_pk_add_f32 v[54:55], v[54:55], v[144:145]
	v_pk_add_f32 v[56:57], v[56:57], v[146:147]
	v_pk_add_f32 v[50:51], v[50:51], v[148:149]
	v_pk_add_f32 v[52:53], v[52:53], v[150:151]
	v_pk_add_f32 v[46:47], v[46:47], v[152:153]
	v_pk_add_f32 v[48:49], v[48:49], v[154:155]
	v_pk_add_f32 v[42:43], v[42:43], v[160:161]
	v_pk_add_f32 v[44:45], v[44:45], v[162:163]
	v_pk_add_f32 v[38:39], v[38:39], v[170:171]
	v_pk_add_f32 v[40:41], v[40:41], v[172:173]
	v_pk_add_f32 v[34:35], v[34:35], v[174:175]
	v_pk_add_f32 v[36:37], v[36:37], v[176:177]
	v_pk_add_f32 v[30:31], v[30:31], v[190:191]
	v_pk_add_f32 v[32:33], v[32:33], v[192:193]
	v_pk_add_f32 v[26:27], v[26:27], v[194:195]
	v_pk_add_f32 v[28:29], v[28:29], v[196:197]
	v_pk_add_f32 v[22:23], v[22:23], v[198:199]
	v_pk_add_f32 v[24:25], v[24:25], v[200:201]
	v_pk_add_f32 v[18:19], v[18:19], v[202:203]
	v_pk_add_f32 v[20:21], v[20:21], v[204:205]
	v_pk_add_f32 v[14:15], v[14:15], v[206:207]
	v_pk_add_f32 v[16:17], v[16:17], v[208:209]
	v_pk_add_f32 v[10:11], v[10:11], v[210:211]
	v_pk_add_f32 v[12:13], v[12:13], v[212:213]
	v_pk_add_f32 v[6:7], v[6:7], v[214:215]
	v_pk_add_f32 v[8:9], v[8:9], v[216:217]
	v_pk_add_f32 v[2:3], v[2:3], v[218:219]
	v_pk_add_f32 v[4:5], v[4:5], v[220:221]
	s_add_u32 s100, s100, 0x50000
	s_addc_u32 s101, s101, 0
	global_store_dwordx4 v131, v[62:65], s[100:101]
	global_store_dwordx4 v131, v[58:61], s[100:101] offset:64
	global_store_dwordx4 v131, v[54:57], s[100:101] offset:512
	global_store_dwordx4 v131, v[50:53], s[100:101] offset:576
	s_add_u32 s100, s100, 0x10000
	s_addc_u32 s101, s101, 0
	global_store_dwordx4 v131, v[46:49], s[100:101]
	global_store_dwordx4 v131, v[42:45], s[100:101] offset:64
	global_store_dwordx4 v131, v[38:41], s[100:101] offset:512
	global_store_dwordx4 v131, v[34:37], s[100:101] offset:576
	s_add_u32 s100, s100, 0x10000
	s_addc_u32 s101, s101, 0
	global_store_dwordx4 v131, v[30:33], s[100:101]
	global_store_dwordx4 v131, v[26:29], s[100:101] offset:64
	global_store_dwordx4 v131, v[22:25], s[100:101] offset:512
	global_store_dwordx4 v131, v[18:21], s[100:101] offset:576
	s_add_u32 s100, s100, 0x10000
	s_addc_u32 s101, s101, 0
	global_store_dwordx4 v131, v[14:17], s[100:101]
	global_store_dwordx4 v131, v[10:13], s[100:101] offset:64
	global_store_dwordx4 v131, v[6:9], s[100:101] offset:512
	global_store_dwordx4 v131, v[2:5], s[100:101] offset:576
	s_add_i32 s2, s2, 1
	s_mov_b64 s[26:27], 0

; __global__ void __launch_bounds__(512, 2) mega(Params P) {
;     ...
;           for (int ai = 0; ai < 2; ++ai)
; #pragma unroll
;             for (int m = 0; m < 4; ++m) {
;               const int row = pm * 256 + ai * 128 + wr * 64 + m * 16 + fr;
; #pragma unroll
;               for (int bj = 0; bj < 2; ++bj)
; #pragma unroll
;                 for (int n = 0; n < 2; ++n) {
;                   const int col = pn * 256 + bj * 128 + wc * 32 + n * 16 + fq * 4;
;                   f32x4* hp = reinterpret_cast<f32x4*>(H + (size_t)row * DM + col);
;                   f32x4 hv = *hp;
;                   const acc4 v = acc[ai][bj][m][n];
;                   hv[0] += v[0]; hv[1] += v[1]; hv[2] += v[2]; hv[3] += v[3];
;                   *hp = hv;
;                 }
;               __builtin_amdgcn_sched_barrier(0);
;             }
.LBB0_1433:
	v_readlane_b32 s10, v255, 58
	s_lshl_b32 s10, s10, 8
	v_readlane_b32 s12, v255, 57
	v_lshl_or_b32 v0, v0, 2, s10
	v_lshl_or_b32 v134, s11, 5, v0
	v_lshl_add_u32 v130, s12, 8, v130
	v_readlane_b32 s48, v255, 4
	v_readlane_b32 s60, v255, 16
	v_readlane_b32 s61, v255, 17
	v_readlane_b32 s49, v255, 5
	v_readlane_b32 s50, v255, 6
	v_readlane_b32 s51, v255, 7
	v_readlane_b32 s52, v255, 8
	v_readlane_b32 s53, v255, 9
	v_readlane_b32 s54, v255, 10
	v_readlane_b32 s55, v255, 11
	v_readlane_b32 s56, v255, 12
	v_readlane_b32 s57, v255, 13
	v_readlane_b32 s58, v255, 14
	v_readlane_b32 s59, v255, 15
	v_readlane_b32 s62, v255, 18
	v_readlane_b32 s63, v255, 19
	v_lshlrev_b32_e32 v131, 12, v130
	v_lshl_add_u32 v131, v134, 2, v131
	s_mov_b64 s[100:101], s[60:61]
	global_load_dwordx4 v[136:139], v131, s[100:101]
	global_load_dwordx4 v[140:143], v131, s[100:101] offset:64
	global_load_dwordx4 v[144:147], v131, s[100:101] offset:512
	global_load_dwordx4 v[148:151], v131, s[100:101] offset:576
	s_add_u32 s100, s100, 0x10000
	s_addc_u32 s101, s101, 0
	global_load_dwordx4 v[152:155], v131, s[100:101]
	global_load_dwordx4 v[160:163], v131, s[100:101] offset:64
	global_load_dwordx4 v[170:173], v131, s[100:101] offset:512
	global_load_dwordx4 v[174:177], v131, s[100:101] offset:576
	s_add_u32 s100, s100, 0x10000
	s_addc_u32 s101, s101, 0
	global_load_dwordx4 v[190:193], v131, s[100:101]
	global_load_dwordx4 v[194:197], v131, s[100:101] offset:64
	global_load_dwordx4 v[198:201], v131, s[100:101] offset:512
	global_load_dwordx4 v[202:205], v131, s[100:101] offset:576
	s_add_u32 s100, s100, 0x10000
	s_addc_u32 s101, s101, 0
	global_load_dwordx4 v[206:209], v131, s[100:101]
	global_load_dwordx4 v[210:213], v131, s[100:101] offset:64
	global_load_dwordx4 v[214:217], v131, s[100:101] offset:512
	global_load_dwordx4 v[218:221], v131, s[100:101] offset:576
	s_waitcnt vmcnt(0)
	v_pk_add_f32 v[126:127], v[126:127], v[136:137]
	v_pk_add_f32 v[128:129], v[128:129], v[138:139]
	v_pk_add_f32 v[118:119], v[118:119], v[140:141]
	v_pk_add_f32 v[120:121], v[120:121], v[142:143]
	v_pk_add_f32 v[122:123], v[122:123], v[144:145]
	v_pk_add_f32 v[124:125], v[124:125], v[146:147]
	v_pk_add_f32 v[114:115], v[114:115], v[148:149]
	v_pk_add_f32 v[116:117], v[116:117], v[150:151]
	v_pk_add_f32 v[110:111], v[110:111], v[152:153]
	v_pk_add_f32 v[112:113], v[112:113], v[154:155]
	v_pk_add_f32 v[102:103], v[102:103], v[160:161]
	v_pk_add_f32 v[104:105], v[104:105], v[162:163]
	v_pk_add_f32 v[106:107], v[106:107], v[170:171]
	v_pk_add_f32 v[108:109], v[108:109], v[172:173]
	v_pk_add_f32 v[98:99], v[98:99], v[174:175]
	v_pk_add_f32 v[100:101], v[100:101], v[176:177]
	v_pk_add_f32 v[94:95], v[94:95], v[190:191]
	v_pk_add_f32 v[96:97], v[96:97], v[192:193]
	v_pk_add_f32 v[86:87], v[86:87], v[194:195]
	v_pk_add_f32 v[88:89], v[88:89], v[196:197]
	v_pk_add_f32 v[90:91], v[90:91], v[198:199]
	v_pk_add_f32 v[92:93], v[92:93], v[200:201]
	v_pk_add_f32 v[82:83], v[82:83], v[202:203]
	v_pk_add_f32 v[84:85], v[84:85], v[204:205]
	v_pk_add_f32 v[78:79], v[78:79], v[206:207]
	v_pk_add_f32 v[80:81], v[80:81], v[208:209]
	v_pk_add_f32 v[70:71], v[70:71], v[210:211]
	v_pk_add_f32 v[72:73], v[72:73], v[212:213]
	v_pk_add_f32 v[74:75], v[74:75], v[214:215]
	v_pk_add_f32 v[76:77], v[76:77], v[216:217]
	v_pk_add_f32 v[66:67], v[66:67], v[218:219]
	v_pk_add_f32 v[68:69], v[68:69], v[220:221]
	s_add_u32 s100, s100, 0x50000
	s_addc_u32 s101, s101, 0
	global_load_dwordx4 v[136:139], v131, s[100:101]
	global_load_dwordx4 v[140:143], v131, s[100:101] offset:64
	global_load_dwordx4 v[144:147], v131, s[100:101] offset:512
	global_load_dwordx4 v[148:151], v131, s[100:101] offset:576
	s_add_u32 s100, s100, 0x10000
	s_addc_u32 s101, s101, 0
	global_load_dwordx4 v[152:155], v131, s[100:101]
	global_load_dwordx4 v[160:163], v131, s[100:101] offset:64
	global_load_dwordx4 v[170:173], v131, s[100:101] offset:512
	global_load_dwordx4 v[174:177], v131, s[100:101] offset:576
	s_add_u32 s100, s100, 0x10000
	s_addc_u32 s101, s101, 0
	global_load_dwordx4 v[190:193], v131, s[100:101]
	global_load_dwordx4 v[194:197], v131, s[100:101] offset:64
	global_load_dwordx4 v[198:201], v131, s[100:101] offset:512
	global_load_dwordx4 v[202:205], v131, s[100:101] offset:576
	s_add_u32 s100, s100, 0x10000
	s_addc_u32 s101, s101, 0
	global_load_dwordx4 v[206:209], v131, s[100:101]
	global_load_dwordx4 v[210:213], v131, s[100:101] offset:64
	global_load_dwordx4 v[214:217], v131, s[100:101] offset:512
	global_load_dwordx4 v[218:221], v131, s[100:101] offset:576
	s_sub_u32 s100, s100, 0xb0000
	s_subb_u32 s101, s101, 0
	global_store_dwordx4 v131, v[126:129], s[100:101]
	global_store_dwordx4 v131, v[118:121], s[100:101] offset:64
	global_store_dwordx4 v131, v[122:125], s[100:101] offset:512
	global_store_dwordx4 v131, v[114:117], s[100:101] offset:576
	s_add_u32 s100, s100, 0x10000
	s_addc_u32 s101, s101, 0
	global_store_dwordx4 v131, v[110:113], s[100:101]
	global_store_dwordx4 v131, v[102:105], s[100:101] offset:64
	global_store_dwordx4 v131, v[106:109], s[100:101] offset:512
	global_store_dwordx4 v131, v[98:101], s[100:101] offset:576
	s_add_u32 s100, s100, 0x10000
	s_addc_u32 s101, s101, 0
	global_store_dwordx4 v131, v[94:97], s[100:101]
	global_store_dwordx4 v131, v[86:89], s[100:101] offset:64
	global_store_dwordx4 v131, v[90:93], s[100:101] offset:512
	global_store_dwordx4 v131, v[82:85], s[100:101] offset:576
	s_add_u32 s100, s100, 0x10000
	s_addc_u32 s101, s101, 0
	global_store_dwordx4 v131, v[78:81], s[100:101]
	global_store_dwordx4 v131, v[70:73], s[100:101] offset:64
	global_store_dwordx4 v131, v[74:77], s[100:101] offset:512
	global_store_dwordx4 v131, v[66:69], s[100:101] offset:576
	s_waitcnt vmcnt(0)
; __global__ void __launch_bounds__(512, 2) mega(Params P) {
;     ...
;           for (int ai = 0; ai < 2; ++ai)
; #pragma unroll
;             for (int m = 0; m < 4; ++m) {
;               const int row = pm * 256 + ai * 128 + wr * 64 + m * 16 + fr;
; #pragma unroll
;               for (int bj = 0; bj < 2; ++bj)
; #pragma unroll
;                 for (int n = 0; n < 2; ++n) {
;                   const int col = pn * 256 + bj * 128 + wc * 32 + n * 16 + fq * 4;
;                   f32x4* hp = reinterpret_cast<f32x4*>(H + (size_t)row * DM + col);
;                   f32x4 hv = *hp;
;                   const acc4 v = acc[ai][bj][m][n];
;                   hv[0] += v[0]; hv[1] += v[1]; hv[2] += v[2]; hv[3] += v[3];
;                   *hp = hv;
;                 }
;               __builtin_amdgcn_sched_barrier(0);
;             }
	v_pk_add_f32 v[62:63], v[62:63], v[136:137]
	v_pk_add_f32 v[64:65], v[64:65], v[138:139]
	v_pk_add_f32 v[58:59], v[58:59], v[140:141]
	v_pk_add_f32 v[60:61], v[60:61], v[142:143]
	v_pk_add_f32 v[54:55], v[54:55], v[144:145]
	v_pk_add_f32 v[56:57], v[56:57], v[146:147]
	v_pk_add_f32 v[50:51], v[50:51], v[148:149]
	v_pk_add_f32 v[52:53], v[52:53], v[150:151]
	v_pk_add_f32 v[46:47], v[46:47], v[152:153]
	v_pk_add_f32 v[48:49], v[48:49], v[154:155]
	v_pk_add_f32 v[42:43], v[42:43], v[160:161]
	v_pk_add_f32 v[44:45], v[44:45], v[162:163]
	v_pk_add_f32 v[38:39], v[38:39], v[170:171]
	v_pk_add_f32 v[40:41], v[40:41], v[172:173]
	v_pk_add_f32 v[34:35], v[34:35], v[174:175]
	v_pk_add_f32 v[36:37], v[36:37], v[176:177]
	v_pk_add_f32 v[30:31], v[30:31], v[190:191]
	v_pk_add_f32 v[32:33], v[32:33], v[192:193]
	v_pk_add_f32 v[26:27], v[26:27], v[194:195]
	v_pk_add_f32 v[28:29], v[28:29], v[196:197]
	v_pk_add_f32 v[22:23], v[22:23], v[198:199]
	v_pk_add_f32 v[24:25], v[24:25], v[200:201]
	v_pk_add_f32 v[18:19], v[18:19], v[202:203]
	v_pk_add_f32 v[20:21], v[20:21], v[204:205]
	v_pk_add_f32 v[14:15], v[14:15], v[206:207]
	v_pk_add_f32 v[16:17], v[16:17], v[208:209]
	v_pk_add_f32 v[10:11], v[10:11], v[210:211]
	v_pk_add_f32 v[12:13], v[12:13], v[212:213]
	v_pk_add_f32 v[6:7], v[6:7], v[214:215]
	v_pk_add_f32 v[8:9], v[8:9], v[216:217]
	v_pk_add_f32 v[2:3], v[2:3], v[218:219]
	v_pk_add_f32 v[4:5], v[4:5], v[220:221]
	s_add_u32 s100, s100, 0x50000
	s_addc_u32 s101, s101, 0
	global_store_dwordx4 v131, v[62:65], s[100:101]
	global_store_dwordx4 v131, v[58:61], s[100:101] offset:64
	global_store_dwordx4 v131, v[54:57], s[100:101] offset:512
	global_store_dwordx4 v131, v[50:53], s[100:101] offset:576
	s_add_u32 s100, s100, 0x10000
	s_addc_u32 s101, s101, 0
	global_store_dwordx4 v131, v[46:49], s[100:101]
	global_store_dwordx4 v131, v[42:45], s[100:101] offset:64
	global_store_dwordx4 v131, v[38:41], s[100:101] offset:512
	global_store_dwordx4 v131, v[34:37], s[100:101] offset:576
	s_add_u32 s100, s100, 0x10000
	s_addc_u32 s101, s101, 0
	global_store_dwordx4 v131, v[30:33], s[100:101]
	global_store_dwordx4 v131, v[26:29], s[100:101] offset:64
	global_store_dwordx4 v131, v[22:25], s[100:101] offset:512
	global_store_dwordx4 v131, v[18:21], s[100:101] offset:576
	s_add_u32 s100, s100, 0x10000
	s_addc_u32 s101, s101, 0
	global_store_dwordx4 v131, v[14:17], s[100:101]
	global_store_dwordx4 v131, v[10:13], s[100:101] offset:64
	global_store_dwordx4 v131, v[6:9], s[100:101] offset:512
	global_store_dwordx4 v131, v[2:5], s[100:101] offset:576
	s_add_i32 s2, s2, 1
	s_mov_b64 s[26:27], 0
